# work-item scheduling: workgroups that ran a chunkB chain skip the prompt-attention queue and go to the sample-scan/attention queues
# speedup vs baseline: 1.0079x; 1.0079x over previous
; #define LAS __attribute__((address_space(3)))
; __device__ __forceinline__ void chunkB_item(const Args& A, LAS unsigned char* lds, int tid, int lane, int wave, int bh) {
;     const int fr = lane & 15, q4 = lane >> 4, mt = wave >> 1, nt0 = (wave & 1) * 2, v0 = mt * 16 + q4 * 4;
;     const int h = bh & 7, b = bh >> 3, colg = h * 64 + v0;
;     const bf16_t* Z = (const bf16_t*)(A.ws + WS_Z); bf16_t* MIX = (bf16_t*)(A.ws + WS_XN);
;     LAS float* ST = (LAS float*)(lds + 18432);
;     f32x4 acc[2] = {{0.f, 0.f, 0.f, 0.f}, {0.f, 0.f, 0.f, 0.f}};
; __global__ void __launch_bounds__(512, 2) hymba_fwd(Args A) {
;     ...
;         for (;;) {
;             if (tid == 0) *s_item = (int)atomicAdd(ctl + CW_WORK + 1, 1u);
;             __syncthreads();
;             const int it = *s_item;
;             __syncthreads();
;             if (it >= N_PB) break;
;             chunkB_item(A, lds, tid, lane, wave, it);
;         }
.LBB0_267:
	s_or_b64 exec, exec, s[4:5]
	s_mov_b32 s98, 0
	v_writelane_b32 v249, s98, 61
	v_readlane_b32 s3, v249, 0
	s_lshr_b32 s9, s3, 7
	v_readlane_b32 s3, v249, 3
	s_lshl_b32 s3, s3, 1
	v_lshrrev_b32_e32 v91, 4, v145
	s_and_b32 s6, s3, 2
	s_lshl_b32 s7, s9, 4
	v_lshlrev_b32_e32 v208, 2, v91
	s_lshl_b32 s3, s6, 4
	s_or_b32 s8, s6, 1
	v_or_b32_e32 v92, s7, v208
	v_writelane_b32 v249, s3, 50
	v_or_b32_e32 v96, s3, v132
	s_add_u32 s3, s96, 0x18b00000
	v_lshlrev_b32_e32 v1, 6, v92
	s_addc_u32 s11, s97, 0
	v_or_b32_e32 v3, 64, v1
	v_lshl_or_b32 v106, s8, 4, v132
	s_add_u32 s24, s96, 0x1cb00000
	v_lshlrev_b32_e32 v93, 1, v132
	v_or_b32_e32 v4, 0x80, v1
	s_addc_u32 s25, s97, 0
	v_lshl_or_b32 v3, s6, 5, v93
	s_lshl_b32 s6, s6, 7
	v_or_b32_e32 v5, 0xc0, v1
	v_or_b32_e32 v1, s7, v132
	s_movk_i32 s7, 0x90
	v_lshl_or_b32 v4, s8, 5, v93
	s_add_i32 s26, s6, 0
	s_lshl_b32 s6, s8, 7
	v_mov_b32_e32 v95, 0
	v_mul_lo_u32 v1, v1, s7
	v_mul_lo_u32 v8, v92, s7
	v_add_u32_e32 v9, 0, v4
	s_lshl_b32 s7, s9, 9
	s_add_i32 s27, s6, 0
	v_lshlrev_b32_e32 v4, 11, v96
	s_add_i32 s26, s26, s7
	s_add_i32 s27, s27, s7
	v_or_b32_e32 v94, 0x8000, v4
	v_mov_b32_e32 v5, v95
	v_writelane_b32 v249, s9, 37
	s_add_u32 s6, s60, 0x1000
	v_lshl_add_u64 v[6:7], s[96:97], 0, v[94:95]
	s_mov_b64 s[8:9], 0xe00000
	v_lshl_add_u64 v[4:5], s[96:97], 0, v[4:5]
	v_lshlrev_b32_e32 v94, 1, v144
	s_addc_u32 s7, s61, 0
	v_lshl_add_u64 v[116:117], v[6:7], 0, s[8:9]
	v_lshl_add_u64 v[118:119], v[4:5], 0, s[8:9]
	v_lshl_add_u64 v[4:5], s[96:97], 0, v[94:95]
	s_mov_b64 s[8:9], 0xb0fe400
	v_mov_b32_e32 v147, v95
	v_lshlrev_b32_e32 v0, 6, v96
	v_lshlrev_b32_e32 v2, 6, v106
	v_add_u32_e32 v1, 0, v1
	v_add_u32_e32 v3, 0, v3
	v_lshlrev_b32_e32 v10, 3, v96
	v_lshlrev_b32_e32 v11, 3, v106
	s_add_u32 s28, s86, 0x8400000
	v_lshl_add_u64 v[120:121], v[4:5], 0, s[8:9]
	v_lshl_add_u64 v[4:5], s[86:87], 0, v[146:147]
	s_mov_b64 s[8:9], 0x8600000
	v_lshlrev_b32_e32 v90, 3, v91
	v_mov_b32_e32 v99, v95
	v_mov_b32_e32 v101, v95
	v_mov_b32_e32 v103, v95
	v_mov_b32_e32 v105, v95
	v_mov_b32_e32 v109, v95
	v_mov_b32_e32 v111, v95
	v_mov_b32_e32 v113, v95
	v_mov_b32_e32 v115, v95
	v_cmp_ne_u32_e64 s[4:5], 0, v96
	v_cmp_gt_u32_e64 s[30:31], 16, v145
	s_addc_u32 s29, s87, 0
	v_add_u32_e32 v97, 0xfffffe00, v144
	v_lshl_add_u64 v[122:123], v[4:5], 0, s[8:9]
	s_add_i32 s34, 0, 0x23ff0
	s_mov_b64 s[8:9], 0x2000
	s_movk_i32 s35, 0x1c00
	s_movk_i32 s36, 0xf000
	v_add_u32_e32 v107, v3, v8
	v_add_u32_e32 v135, v9, v8
	v_add_u32_e32 v139, v1, v89
	v_mbcnt_hi_u32_b32 v209, -1, v162
	v_add_u32_e32 v141, 0, v10
	s_mov_b32 s10, 0x3c800000
	v_add_u32_e32 v143, 0, v11
	s_movk_i32 s37, 0x47f
	v_mov_b32_e32 v147, 0x1c00
	v_mov_b32_e32 v163, 0xe00000
	v_mov_b32_e32 v173, 0x1a00
	v_bfe_u32 v0, v144, 6, 1
	v_lshlrev_b32_e32 v124, 12, v0
	v_add_u32_e32 v126, 0x800, v124
	v_lshrrev_b32_e32 v1, 7, v144
	v_lshlrev_b32_e32 v98, 10, v1
	v_lshl_add_u32 v98, v0, 9, v98
	v_and_b32_e32 v2, 63, v144
	v_add_u32_e32 v98, v98, v2
	v_add_u32_e32 v100, 64, v98
	v_add_u32_e32 v102, 0x80, v98
	v_add_u32_e32 v104, 0xc0, v98
	v_add_u32_e32 v108, 0x100, v98
	v_add_u32_e32 v110, 0x140, v98
	v_add_u32_e32 v112, 0x180, v98
	v_add_u32_e32 v114, 0x1c0, v98
	v_lshlrev_b32_e32 v148, 9, v1
	v_bfe_u32 v2, v144, 5, 1
	v_lshl_add_u32 v148, v2, 8, v148
	v_and_b32_e32 v2, 15, v144
	v_lshl_add_u32 v148, v2, 4, v148
	v_bfe_u32 v2, v144, 4, 1
	v_lshl_add_u32 v148, v2, 3, v148
	s_barrier
	s_branch .LBB0_271

; #define LAS __attribute__((address_space(3)))
; __device__ __forceinline__ void chunkB_item(const Args& A, LAS unsigned char* lds, int tid, int lane, int wave, int bh) {
;     const int fr = lane & 15, q4 = lane >> 4, mt = wave >> 1, nt0 = (wave & 1) * 2, v0 = mt * 16 + q4 * 4;
;     const int h = bh & 7, b = bh >> 3, colg = h * 64 + v0;
;     const bf16_t* Z = (const bf16_t*)(A.ws + WS_Z); bf16_t* MIX = (bf16_t*)(A.ws + WS_XN);
;     LAS float* ST = (LAS float*)(lds + 18432);
;     f32x4 acc[2] = {{0.f, 0.f, 0.f, 0.f}, {0.f, 0.f, 0.f, 0.f}};
; __global__ void __launch_bounds__(512, 2) hymba_fwd(Args A) {
;     ...
;             if (tid == 0) *s_item = (int)atomicAdd(ctl + CW_WORK + 1, 1u);
;             __syncthreads();
;             const int it = *s_item;
;             __syncthreads();
;             if (it >= N_PB) break;
;             chunkB_item(A, lds, tid, lane, wave, it);
.LBB0_275:
	s_or_b64 exec, exec, s[12:13]
	v_mov_b32_e32 v0, s34
	s_waitcnt lgkmcnt(0)
	s_barrier
	ds_read_b32 v0, v0
	s_movk_i32 s13, 0x7f
	s_mov_b64 s[14:15], -1
	s_waitcnt lgkmcnt(0)
	s_barrier
	v_cmp_lt_i32_e32 vcc, s13, v0
	v_readfirstlane_b32 s12, v0
	s_cbranch_vccnz .LBB0_270
	s_mov_b32 s98, 1
	v_writelane_b32 v249, s98, 61
	s_lshr_b32 s98, s12, 3
	s_mul_i32 s98, s98, 0xe00000
	s_add_u32 s98, s94, s98
	s_addc_u32 s99, s95, 0
	s_sub_u32 s98, s98, 0x1c00
	s_subb_u32 s99, s99, 0
	v_lshrrev_b32_e32 v240, 4, v144
	v_lshrrev_b32_e32 v241, 6, v144
	v_lshl_add_u32 v240, v241, 2, v240
	v_and_b32_e32 v241, 15, v144
	v_mul_u32_u24_e32 v242, 0x90, v240
	v_lshl_add_u32 v242, v241, 3, v242
	v_add_u32_e32 v242, 0x6000, v242
	v_mul_u32_u24_e32 v240, 0x1c00, v240
	v_lshl_add_u32 v240, v241, 3, v240
	s_and_b32 s22, s12, 7
	s_lshl_b32 s22, s22, 7
	s_add_i32 s22, s22, 0x800
	v_add_u32_e32 v240, s22, v240
	v_add_u32_e32 v240, 0x1c00, v240
	v_add_u32_e32 v241, 0x7000, v240
	v_mul_u32_u24_e32 v243, 0x90, v96
	v_lshl_add_u32 v243, v92, 1, v243
	v_add_u32_e32 v243, 0x6000, v243
	global_load_dwordx2 v[182:183], v240, s[98:99]
	global_load_dwordx2 v[188:189], v241, s[98:99]
	global_load_dwordx2 v[184:185], v240, s[98:99] offset:1280
	global_load_dwordx2 v[190:191], v241, s[98:99] offset:1280
	s_and_b32 s38, s12, 7
	v_mov_b32_e32 v244, s38
	v_lshl_add_u32 v244, v244, 6, v92
	v_lshlrev_b32_e32 v244, 2, v244
	v_readlane_b32 s20, v249, 10
	v_readlane_b32 s21, v249, 11
	v_readlane_b32 s22, v249, 12
	v_readlane_b32 s23, v249, 13
	s_nop 4
	global_load_dwordx4 v[228:231], v244, s[20:21]
	global_load_dwordx4 v[250:253], v244, s[22:23]
	global_load_dwordx2 v[232:233], v244, s[6:7]
	global_load_dwordx2 v[254:255], v244, s[6:7] offset:8
	s_ashr_i32 s13, s12, 31
	s_mul_i32 s14, s12, 0xc0000
	s_mul_hi_i32 s15, s12, 0xc0000
	s_add_u32 s14, s86, s14
	s_addc_u32 s15, s87, s15
	s_add_u32 s16, s14, 0x2000
	v_lshlrev_b32_e32 v94, 8, v91
	v_lshl_add_u32 v94, v132, 4, v94
	v_add_u32_e32 v234, v94, v124
	v_add_u32_e32 v235, v94, v126
	v_lshrrev_b32_e32 v236, 7, v144
	v_lshlrev_b32_e32 v236, 12, v236
	v_bfe_u32 v237, v144, 6, 1
	v_lshl_add_u32 v236, v237, 11, v236
	v_and_b32_e32 v237, 63, v144
	v_lshl_add_u32 v236, v237, 4, v236
	v_add_u32_e32 v236, 0x2000, v236
	v_add_u32_e32 v237, 0x400, v236
	v_add_u32_e32 v238, v148, v124
	v_add_u32_e32 v238, 0x2000, v238
	v_add_u32_e32 v239, v148, v126
	v_add_u32_e32 v239, 0x2000, v239
	v_mul_u32_u24_e32 v245, 0x1c00, v96
	v_lshl_add_u32 v245, v92, 1, v245
	v_mov_b32_e32 v246, s38
	v_lshl_add_u32 v245, v246, 7, v245
	v_add_u32_e32 v245, 0x800, v245
	v_lshlrev_b32_e32 v246, 4, v144
	v_bfe_u32 v247, v144, 6, 1
	v_lshlrev_b32_e32 v247, 12, v247
	v_and_b32_e32 v156, 63, v144
	v_lshl_add_u32 v247, v156, 4, v247
	global_load_dwordx4 v[210:213], v236, s[14:15]
	global_load_dwordx4 v[40:43], v237, s[14:15]
	global_load_dwordx4 v[0:3], v246, s[14:15]
	s_addc_u32 s17, s15, 0
	v_lshl_add_u64 v[8:9], s[14:15], 0, v[94:95]
	v_mov_b32_e32 v125, v95
	v_mov_b32_e32 v127, v95
	v_lshl_add_u64 v[4:5], v[8:9], 0, v[124:125]
	v_lshl_add_u64 v[10:11], v[98:99], 2, s[16:17]
	v_lshl_add_u64 v[12:13], v[100:101], 2, s[16:17]
	v_lshl_add_u64 v[14:15], v[102:103], 2, s[16:17]
	v_lshl_add_u64 v[8:9], v[8:9], 0, v[126:127]
	s_nop 0
	v_lshl_add_u64 v[16:17], v[104:105], 2, s[16:17]
	v_lshl_add_u64 v[8:9], v[108:109], 2, s[16:17]
	v_lshl_add_u64 v[10:11], v[110:111], 2, s[16:17]
	v_lshl_add_u64 v[12:13], v[112:113], 2, s[16:17]
	v_lshl_add_u64 v[14:15], v[114:115], 2, s[16:17]
	s_ashr_i32 s14, s12, 3
	s_lshl_b64 s[16:17], s[12:13], 19
	s_add_u32 s18, s3, s16
	s_addc_u32 s19, s11, s17
	v_mov_b32_e32 v149, v95
	v_lshl_add_u64 v[8:9], s[18:19], 0, v[148:149]
	s_ashr_i32 s15, s14, 31
	v_lshl_add_u64 v[16:17], s[18:19], 0, v[94:95]
	v_lshl_add_u64 v[18:19], v[8:9], 0, s[8:9]
	s_lshl_b64 s[16:17], s[14:15], 11
	v_lshl_add_u64 v[12:13], v[16:17], 0, v[124:125]
	v_lshl_add_u64 v[24:25], v[18:19], 0, v[124:125]
	global_load_dwordx4 v[8:11], v246, s[18:19]
	s_nop 0
	v_or_b32_e32 v27, s16, v96
	global_load_dwordx2 v[196:197], v[24:25], off
	v_mov_b64_e32 v[24:25], s[94:95]
	v_lshl_add_u32 v26, s38, 6, v92
	v_mad_u64_u32 v[24:25], s[18:19], v27, s35, v[24:25]
	v_mad_i32_i24 v25, s17, v147, v25
	v_lshlrev_b32_e32 v150, 1, v26
	v_mov_b32_e32 v151, v95
	v_lshl_add_u64 v[24:25], v[24:25], 0, v[150:151]
	global_load_dwordx2 v[174:175], v[24:25], off offset:2048
	v_mov_b32_e32 v170, v95
	v_mov_b32_e32 v171, v95
	s_and_saveexec_b64 s[18:19], s[4:5]
	s_cbranch_execz .LBB0_278
	v_add_co_u32_e32 v28, vcc, 0xfffff000, v24
	s_nop 1
	v_addc_co_u32_e32 v29, vcc, -1, v25, vcc
	global_load_dwordx2 v[170:171], v[28:29], off offset:-1024

; #define LAS __attribute__((address_space(3)))
; __device__ __forceinline__ void attn_prompt_item(const Args& A, LAS unsigned char* lds, int tid, int lane, int wave, int b, int nb, int kvh) {
;     const bf16_t* Z = (const bf16_t*)(A.ws + WS_Z); bf16_t* MIX = (bf16_t*)(A.ws + WS_XN);
;     const float* ct = (const float*)(A.ws + WS_ROPE); const float* st = ct + 2056 * 8;
;     const int fr = lane & 15, q4 = lane >> 4;
; __global__ void __launch_bounds__(512, 2) hymba_fwd(Args A) {
;     ...
;         for (;;) {
;             if (tid == 0) *s_item = (int)atomicAdd(ctl + CW_WORK + 3, 1u);
;             __syncthreads();
;             const int r = *s_item;
;             __syncthreads();
;             if (r >= N_PA) break;
;             const int kvh = r & 1, nb = (r >> 1) & 15, b = r >> 5;
;             attn_prompt_item(A, lds, tid, lane, wave, b, nb, kvh);
;         }
.LBB0_287:
	s_add_u32 s88, s96, 0xd00000
	s_addc_u32 s89, s97, 0
	s_add_u32 s90, s96, 0xd10100
	s_movk_i32 s4, 0xff72
	s_addc_u32 s91, s97, 0
	s_movk_i32 s3, 0xff80
	v_mul_i32_i24_sdwa v1, v144, s4 dst_sel:DWORD dst_unused:UNUSED_PAD src0_sel:BYTE_0 src1_sel:DWORD
	v_readlane_b32 s9, v249, 0
	v_readlane_b32 s4, v249, 3
	v_add_u32_sdwa v65, v144, s3 dst_sel:DWORD dst_unused:UNUSED_PAD src0_sel:BYTE_0 src1_sel:DWORD
	s_movk_i32 s3, 0x7f
	s_cmpk_lt_u32 s9, 0x400
	s_mulk_i32 s4, 0x900
	v_cmp_gt_u32_sdwa s[40:41], v144, s3 src0_sel:BYTE_0 src1_sel:DWORD
	s_movk_i32 s3, 0x90
	s_cselect_b64 s[44:45], -1, 0
	s_add_i32 s4, s4, 0
	v_mul_u32_u24_sdwa v0, v144, s3 dst_sel:DWORD dst_unused:UNUSED_PAD src0_sel:BYTE_0 src1_sel:DWORD
	s_add_i32 s8, s4, 0x11400
	v_add3_u32 v69, 0, v0, v1
	v_mov_b32_e32 v1, s8
	v_mad_u32_u24 v3, v132, s3, v1
	s_add_u32 s3, s96, 0xe00400
	v_add_u32_e32 v2, s8, v93
	s_addc_u32 s51, s97, 0
	s_bfe_u32 s8, s9, 0x20006
	s_lshl_b32 s9, s8, 5
	s_cmp_gt_u32 s8, 1
	v_or_b32_e32 v68, s9, v208
	v_or_b32_e32 v71, s9, v132
	s_cselect_b64 s[8:9], -1, 0
	v_cndmask_b32_e64 v1, 0, 1, s[8:9]
	v_lshrrev_b32_e32 v72, 8, v144
	v_lshrrev_b32_e32 v7, 8, v144
	v_mov_b32_e32 v67, 0
	v_readfirstlane_b32 s52, v1
	s_and_b64 s[8:9], s[8:9], exec
	v_lshlrev_b32_e32 v1, 4, v72
	v_lshlrev_b32_e32 v66, 4, v7
	v_add3_u32 v75, v0, v1, 0
	v_lshl_add_u64 v[0:1], s[96:97], 0, v[66:67]
	s_mov_b64 s[8:9], 0xa301500
	v_lshlrev_b32_e32 v66, 5, v7
	v_mul_u32_u24_e32 v6, 0x210, v88
	v_lshl_add_u64 v[86:87], v[0:1], 0, s[8:9]
	v_lshl_add_u64 v[0:1], s[86:87], 0, v[66:67]
	s_mov_b64 s[8:9], 0x871a010
	v_mul_u32_u24_e32 v5, 0x210, v132
	v_lshl_add_u64 v[92:93], v[0:1], 0, s[8:9]
	v_add3_u32 v0, v6, v89, 0
	v_add_u32_e32 v77, 0x9000, v0
	v_add3_u32 v0, v5, v89, 0
	v_add_u32_e32 v79, 0x9000, v0
	v_sub_u32_e32 v0, v68, v132
	s_cselect_b32 s53, 4, 3
	v_mul_u32_u24_e32 v4, 0x240, v91
	v_add_u32_e32 v81, 19, v0
	v_mul_u32_u24_e32 v0, 0x90, v132
	s_add_i32 s54, 0, 0x23ff0
	s_mov_b32 s43, 0
	v_cmp_gt_u32_e64 s[4:5], 32, v145
	v_cmp_lt_u32_e64 s[6:7], 31, v145
	v_xor_b32_e32 v64, 8, v90
	v_or_b32_e32 v70, 1, v68
	v_or_b32_e32 v74, 2, v68
	v_or_b32_e32 v76, 3, v68
	v_or_b32_e32 v78, 16, v68
	v_or_b32_e32 v80, 17, v68
	v_or_b32_e32 v82, 18, v68
	v_or_b32_e32 v84, 19, v68
	v_lshlrev_b32_e32 v73, 3, v72
	v_add3_u32 v83, v0, v89, 0
	s_movk_i32 s55, 0x1ff
	s_movk_i32 s56, 0x1c00
	s_mov_b64 s[46:47], 0x1100
	s_mov_b32 s48, 0x3e38aa3b
	s_movk_i32 s57, 0xff7f
	s_mov_b32 s58, 0xf149f2ca
	v_add_u32_e32 v85, v2, v4
	v_add_u32_e32 v91, v3, v89
	v_lshlrev_b32_e32 v88, 1, v88
	v_mov_b32_e32 v135, s54
	v_mov_b32_e32 v139, 0xe00000
	v_mov_b32_e32 v141, 0x1c00
	v_mov_b32_e32 v143, 0xf149f2ca
	v_readlane_b32 s98, v249, 61
	s_cmp_eq_u32 s98, 0
	s_cbranch_scc1 .LBB0_290
	s_branch .LBB0_316
